# attention: inverted static wave-priority split (waves 0-3 at priority 1 instead of waves 4-7)
# baseline (speedup 1.0000x reference)
.LBB0_529:
	v_readfirstlane_b32 s2, v214
	s_cmpk_gt_i32 s2, 0xff
	s_cbranch_scc1 .LBB0_531
	s_setprio 1
